# speedup vs baseline: 1.0086x; 1.0086x over previous
; #define GAS __attribute__((address_space(1)))
; __device__ __forceinline__ int ugrid() { return __builtin_amdgcn_readfirstlane((int)gridDim.x); }
; __device__ __forceinline__ int ubid() { return __builtin_amdgcn_readfirstlane((int)blockIdx.x); }
; __device__ __forceinline__ void phase_inproj() {
;     ...
;       for (int r0 = ubid() * 64 + w * 16; r0 < T; r0 += ugrid() * 64) {
;         const GAS bf16x8* ap = (const GAS bf16x8*)(xg + (size_t)(r0 + fr_) * DM + fq_ * 8);
;         const GAS bf16x8* bp = (const GAS bf16x8*)(wf + (size_t)(fr_ & 7) * DM + fq_ * 8);
;         f32x4 c = {0.f, 0.f, 0.f, 0.f};
; #pragma unroll
;         for (int kb = 0; kb < 2; ++kb) {
;           bf16x8 a[16], b[16];
; #pragma unroll
;           for (int k = 0; k < 16; ++k) { a[k] = ap[(kb * 16 + k) * 4]; b[k] = bp[(kb * 16 + k) * 4]; }
; #pragma unroll
;           for (int k = 0; k < 16; ++k) c = __builtin_amdgcn_mfma_f32_16x16x32_bf16(a[k], b[k], c, 0, 0, 0);
;         }
.LBB0_378:
	v_or_b32_e32 v2, v7, v6
	v_ashrrev_i32_e32 v3, 31, v2
	v_lshlrev_b64 v[2:3], 11, v[2:3]
	v_lshl_add_u64 v[86:87], v[10:11], 0, v[2:3]
	s_load_dwordx2 s[4:5], s[6:7], 0x40
	global_load_dwordx4 v[14:17], v[86:87], off
	global_load_dwordx4 v[26:29], v[12:13], off
	global_load_dwordx4 v[30:33], v[86:87], off offset:64
	global_load_dwordx4 v[34:37], v[12:13], off offset:64
	global_load_dwordx4 v[38:41], v[86:87], off offset:128
	global_load_dwordx4 v[42:45], v[12:13], off offset:128
	global_load_dwordx4 v[46:49], v[86:87], off offset:192
	global_load_dwordx4 v[50:53], v[12:13], off offset:192
	global_load_dwordx4 v[54:57], v[86:87], off offset:256
	global_load_dwordx4 v[58:61], v[12:13], off offset:256
	global_load_dwordx4 v[62:65], v[86:87], off offset:320
	global_load_dwordx4 v[66:69], v[12:13], off offset:320
	global_load_dwordx4 v[70:73], v[86:87], off offset:384
	global_load_dwordx4 v[74:77], v[12:13], off offset:384
	global_load_dwordx4 v[78:81], v[86:87], off offset:448
	global_load_dwordx4 v[82:85], v[12:13], off offset:448
	global_load_dwordx4 v[88:91], v[86:87], off offset:512
	global_load_dwordx4 v[92:95], v[12:13], off offset:512
	global_load_dwordx4 v[96:99], v[86:87], off offset:576
	global_load_dwordx4 v[100:103], v[12:13], off offset:576
	global_load_dwordx4 v[104:107], v[86:87], off offset:640
	global_load_dwordx4 v[108:111], v[12:13], off offset:640
	global_load_dwordx4 v[112:115], v[86:87], off offset:704
	global_load_dwordx4 v[116:119], v[12:13], off offset:704
	global_load_dwordx4 v[120:123], v[86:87], off offset:768
	global_load_dwordx4 v[124:127], v[12:13], off offset:768
	global_load_dwordx4 v[128:131], v[86:87], off offset:832
	global_load_dwordx4 v[132:135], v[12:13], off offset:832
	global_load_dwordx4 v[136:139], v[86:87], off offset:896
	global_load_dwordx4 v[140:143], v[12:13], off offset:896
	global_load_dwordx4 v[144:147], v[86:87], off offset:960
	global_load_dwordx4 v[148:151], v[12:13], off offset:960
	global_load_dwordx4 v[152:155], v[86:87], off offset:1024
	global_load_dwordx4 v[156:159], v[12:13], off offset:1024
	global_load_dwordx4 v[160:163], v[86:87], off offset:1088
	global_load_dwordx4 v[164:167], v[12:13], off offset:1088
	global_load_dwordx4 v[176:179], v[86:87], off offset:1152
	global_load_dwordx4 v[180:183], v[12:13], off offset:1152
	global_load_dwordx4 v[184:187], v[86:87], off offset:1216
	global_load_dwordx4 v[188:191], v[12:13], off offset:1216
	global_load_dwordx4 v[192:195], v[86:87], off offset:1280
	global_load_dwordx4 v[196:199], v[12:13], off offset:1280
	global_load_dwordx4 v[200:203], v[86:87], off offset:1344
	global_load_dwordx4 v[204:207], v[12:13], off offset:1344
	global_load_dwordx4 v[208:211], v[86:87], off offset:1408
	global_load_dwordx4 v[212:215], v[12:13], off offset:1408
	global_load_dwordx4 v[216:219], v[86:87], off offset:1472
	global_load_dwordx4 v[220:223], v[12:13], off offset:1472
	global_load_dwordx4 v[224:227], v[86:87], off offset:1536
	global_load_dwordx4 v[228:231], v[12:13], off offset:1536
	global_load_dwordx4 v[232:235], v[86:87], off offset:1600
	global_load_dwordx4 v[236:239], v[12:13], off offset:1600
	s_waitcnt vmcnt(40)
	v_mfma_f32_16x16x32_bf16 v[2:5], v[14:17], v[26:29], 0
	v_mfma_f32_16x16x32_bf16 v[2:5], v[30:33], v[34:37], v[2:5]
	v_mfma_f32_16x16x32_bf16 v[2:5], v[38:41], v[42:45], v[2:5]
	v_mfma_f32_16x16x32_bf16 v[2:5], v[46:49], v[50:53], v[2:5]
	v_mfma_f32_16x16x32_bf16 v[2:5], v[54:57], v[58:61], v[2:5]
	v_mfma_f32_16x16x32_bf16 v[2:5], v[62:65], v[66:69], v[2:5]
	global_load_dwordx4 v[14:17], v[86:87], off offset:1664
	global_load_dwordx4 v[26:29], v[12:13], off offset:1664
	global_load_dwordx4 v[30:33], v[86:87], off offset:1728
	global_load_dwordx4 v[34:37], v[12:13], off offset:1728
	global_load_dwordx4 v[38:41], v[86:87], off offset:1792
	global_load_dwordx4 v[42:45], v[12:13], off offset:1792
	global_load_dwordx4 v[46:49], v[86:87], off offset:1856
	global_load_dwordx4 v[50:53], v[12:13], off offset:1856
	global_load_dwordx4 v[54:57], v[86:87], off offset:1920
	global_load_dwordx4 v[58:61], v[12:13], off offset:1920
	global_load_dwordx4 v[62:65], v[86:87], off offset:1984
	global_load_dwordx4 v[66:69], v[12:13], off offset:1984
	s_waitcnt vmcnt(50)
	v_mfma_f32_16x16x32_bf16 v[2:5], v[70:73], v[74:77], v[2:5]
	s_waitcnt vmcnt(48)
	v_mfma_f32_16x16x32_bf16 v[2:5], v[78:81], v[82:85], v[2:5]
	s_waitcnt vmcnt(46)
	v_mfma_f32_16x16x32_bf16 v[2:5], v[88:91], v[92:95], v[2:5]
	s_waitcnt vmcnt(44)
	v_mfma_f32_16x16x32_bf16 v[2:5], v[96:99], v[100:103], v[2:5]
	s_waitcnt vmcnt(42)
	v_mfma_f32_16x16x32_bf16 v[2:5], v[104:107], v[108:111], v[2:5]
	s_waitcnt vmcnt(40)
	v_mfma_f32_16x16x32_bf16 v[2:5], v[112:115], v[116:119], v[2:5]
	s_waitcnt vmcnt(38)
	v_mfma_f32_16x16x32_bf16 v[2:5], v[120:123], v[124:127], v[2:5]
	s_waitcnt vmcnt(36)
	v_mfma_f32_16x16x32_bf16 v[2:5], v[128:131], v[132:135], v[2:5]
	s_waitcnt vmcnt(34)
	v_mfma_f32_16x16x32_bf16 v[2:5], v[136:139], v[140:143], v[2:5]
	s_waitcnt vmcnt(32)
	v_mfma_f32_16x16x32_bf16 v[2:5], v[144:147], v[148:151], v[2:5]
	s_waitcnt vmcnt(30)
	v_mfma_f32_16x16x32_bf16 v[2:5], v[152:155], v[156:159], v[2:5]
	s_waitcnt vmcnt(28)
	v_mfma_f32_16x16x32_bf16 v[2:5], v[160:163], v[164:167], v[2:5]
	s_waitcnt vmcnt(26)
	v_mfma_f32_16x16x32_bf16 v[2:5], v[176:179], v[180:183], v[2:5]
	s_waitcnt vmcnt(24)
	v_mfma_f32_16x16x32_bf16 v[2:5], v[184:187], v[188:191], v[2:5]
	s_waitcnt vmcnt(22)
	v_mfma_f32_16x16x32_bf16 v[2:5], v[192:195], v[196:199], v[2:5]
	s_waitcnt vmcnt(20)
	v_mfma_f32_16x16x32_bf16 v[2:5], v[200:203], v[204:207], v[2:5]
	s_waitcnt vmcnt(18)
	v_mfma_f32_16x16x32_bf16 v[2:5], v[208:211], v[212:215], v[2:5]
	s_waitcnt vmcnt(16)
	v_mfma_f32_16x16x32_bf16 v[2:5], v[216:219], v[220:223], v[2:5]
	s_waitcnt vmcnt(14)
	v_mfma_f32_16x16x32_bf16 v[2:5], v[224:227], v[228:231], v[2:5]
	s_waitcnt vmcnt(12)
	v_mfma_f32_16x16x32_bf16 v[2:5], v[232:235], v[236:239], v[2:5]
	s_waitcnt vmcnt(10)
	v_mfma_f32_16x16x32_bf16 v[2:5], v[14:17], v[26:29], v[2:5]
	s_waitcnt vmcnt(8)
	v_mfma_f32_16x16x32_bf16 v[2:5], v[30:33], v[34:37], v[2:5]
	s_waitcnt vmcnt(6)
	v_mfma_f32_16x16x32_bf16 v[2:5], v[38:41], v[42:45], v[2:5]
	s_waitcnt vmcnt(4)
	v_mfma_f32_16x16x32_bf16 v[2:5], v[46:49], v[50:53], v[2:5]
	s_waitcnt vmcnt(2)
	v_mfma_f32_16x16x32_bf16 v[2:5], v[54:57], v[58:61], v[2:5]
	s_waitcnt vmcnt(0)
	v_mfma_f32_16x16x32_bf16 v[2:5], v[62:65], v[66:69], v[2:5]
	s_and_saveexec_b64 s[12:13], vcc
	s_cbranch_execz .LBB0_377
; #define GAS __attribute__((address_space(1)))
; __device__ __forceinline__ void phase_inproj() {
;     ...
;         if (fr_ < 8) {
;           const float bias = ((const GAS float*)P.forget_bias)[fr_];
; #pragma unroll
;           for (int i = 0; i < 4; ++i) {
;             const int row = r0 + fq_ * 4 + i;
;             const GAS f32x4* sp = (const GAS f32x4*)(ssq + (size_t)row * 16);
;             const f32x4 s0 = sp[0], s1 = sp[1], s2 = sp[2], s3 = sp[3];
;             const float t = ((s0.x + s0.y) + (s0.z + s0.w)) + ((s1.x + s1.y) + (s1.z + s1.w)) + ((s2.x + s2.y) + (s2.z + s2.w)) + ((s3.x + s3.y) + (s3.z + s3.w));
;             const float l = c[i] * rsqrtf(t * (1.f / DM) + EPS) + bias;
;             const float ls = fminf(l, 0.f) - log1pf(__expf(-fabsf(l)));
;             logf2[(size_t)((row >> 13) * 8 + fr_) * SEQ + (row & (SEQ - 1))] = ls * LOG2E;
;           }
	v_or_b32_e32 v14, v7, v18
	v_ashrrev_i32_e32 v15, 31, v14
	v_lshlrev_b64 v[16:17], 6, v[14:15]
	v_lshl_add_u64 v[16:17], s[8:9], 0, v[16:17]
	global_load_dwordx4 v[26:29], v[16:17], off
	global_load_dwordx4 v[30:33], v[16:17], off offset:16
	global_load_dwordx4 v[34:37], v[16:17], off offset:32
	global_load_dwordx4 v[38:41], v[16:17], off offset:48
	v_ashrrev_i32_e32 v8, 10, v7
	v_bitop3_b32 v17, v7, s23, v18 bitop3:0xc8
	v_and_or_b32 v16, v8, -8, v6
	v_lshlrev_b32_e32 v8, 2, v17
	s_waitcnt lgkmcnt(0)
	global_load_dword v15, v19, s[4:5]
	v_or_b32_e32 v42, 1, v14
	v_ashrrev_i32_e32 v17, 31, v16
	v_ashrrev_i32_e32 v43, 31, v42
	v_lshlrev_b64 v[16:17], 15, v[16:17]
	v_lshl_add_u64 v[16:17], s[16:17], 0, v[16:17]
	s_waitcnt vmcnt(4)
	v_mov_b32_e32 v44, v27
	v_mov_b32_e32 v45, v28
	v_mov_b32_e32 v27, v29
	s_waitcnt vmcnt(3)
	v_mov_b32_e32 v28, v31
	v_mov_b32_e32 v29, v32
	v_mov_b32_e32 v31, v33
	v_pk_add_f32 v[26:27], v[44:45], v[26:27]
	v_pk_add_f32 v[28:29], v[28:29], v[30:31]
	v_pk_add_f32 v[26:27], v[26:27], v[26:27] op_sel:[0,1] op_sel_hi:[1,0]
	v_pk_add_f32 v[28:29], v[28:29], v[28:29] op_sel:[0,1] op_sel_hi:[1,0]
	s_waitcnt vmcnt(2)
	v_add_f32_e32 v32, v34, v35
	v_add_f32_e32 v34, v36, v37
	s_waitcnt vmcnt(1)
	v_mov_b32_e32 v33, v40
	v_mov_b32_e32 v35, v41
	v_mov_b32_e32 v27, v38
	v_mov_b32_e32 v29, v39
	v_pk_add_f32 v[30:31], v[32:33], v[34:35]
	v_pk_add_f32 v[26:27], v[26:27], v[28:29]
	s_nop 0
	v_pk_add_f32 v[26:27], v[26:27], v[30:31]
	s_nop 0
	v_add_f32_e32 v25, v26, v27
	v_fmamk_f32 v25, v25, 0x3a800000, v20
	v_mul_f32_e32 v26, 0x4b800000, v25
	v_cmp_gt_f32_e64 s[4:5], s3, v25
	s_nop 1
	v_cndmask_b32_e64 v25, v25, v26, s[4:5]
	v_rsq_f32_e32 v25, v25
	v_lshlrev_b64 v[26:27], 6, v[42:43]
	v_lshl_add_u64 v[42:43], s[8:9], 0, v[26:27]
	v_lshl_add_u64 v[26:27], v[16:17], 0, v[8:9]
	v_mul_f32_e32 v28, 0x45800000, v25
	v_cndmask_b32_e64 v25, v25, v28, s[4:5]
	s_waitcnt vmcnt(0)
	v_fma_f32 v2, v2, v25, v15
	v_mul_f32_e64 v25, |v2|, s18
	v_exp_f32_e32 v25, v25
	v_min_f32_e32 v2, 0, v2
	v_add_f32_e32 v8, 1.0, v25
	v_add_f32_e32 v30, -1.0, v8
	v_frexp_mant_f32_e32 v31, v8
	v_cvt_f64_f32_e32 v[28:29], v8
	v_sub_f32_e32 v32, v30, v8
	v_frexp_exp_i32_f64_e32 v28, v[28:29]
	v_cmp_gt_f32_e64 s[4:5], s19, v31
	v_sub_f32_e32 v30, v25, v30
	v_add_f32_e32 v29, 1.0, v32
	v_subbrev_co_u32_e64 v28, s[4:5], 0, v28, s[4:5]
	v_add_f32_e32 v29, v30, v29
	v_sub_u32_e32 v30, 0, v28
	v_cvt_f32_i32_e32 v28, v28
	v_ldexp_f32 v8, v8, v30
	v_ldexp_f32 v29, v29, v30
	v_add_f32_e32 v30, -1.0, v8
	v_add_f32_e32 v31, 1.0, v8
	v_add_f32_e32 v32, 1.0, v30
	v_add_f32_e32 v33, -1.0, v31
	v_sub_f32_e32 v32, v8, v32
	v_sub_f32_e32 v8, v8, v33
	v_mul_f32_e32 v33, 0x3f317218, v28
	v_add_f32_e32 v32, v29, v32
	v_add_f32_e32 v8, v29, v8
	v_fma_f32 v29, v28, s20, -v33
	v_add_f32_e32 v34, v30, v32
	v_add_f32_e32 v35, v31, v8
	v_fmac_f32_e32 v29, 0xb102e308, v28
	v_sub_f32_e32 v28, v34, v30
	v_sub_f32_e32 v30, v35, v31
	v_rcp_f32_e32 v31, v35
	v_add_f32_e32 v36, v33, v29
	v_sub_f32_e32 v8, v8, v30
	v_sub_f32_e32 v30, v36, v33
	v_sub_f32_e32 v29, v29, v30
	v_mul_f32_e32 v30, v34, v31
	v_sub_f32_e32 v28, v32, v28
	v_mul_f32_e32 v32, v35, v30
	v_fma_f32 v33, v30, v35, -v32
	v_fmac_f32_e32 v33, v30, v8
	v_add_f32_e32 v37, v32, v33
	v_sub_f32_e32 v38, v34, v37
	v_sub_f32_e32 v32, v37, v32
	v_sub_f32_e32 v34, v34, v38
	v_sub_f32_e32 v32, v32, v33
	v_sub_f32_e32 v33, v34, v37
	v_add_f32_e32 v28, v28, v33
	v_add_f32_e32 v28, v32, v28
	v_add_f32_e32 v32, v38, v28
	v_mul_f32_e32 v33, v31, v32
	v_sub_f32_e32 v34, v38, v32
	v_mul_f32_e32 v37, v35, v33
	v_add_f32_e32 v28, v28, v34
	v_add_f32_e32 v34, v30, v33
	v_fma_f32 v35, v33, v35, -v37
	v_sub_f32_e32 v30, v34, v30
	v_fmac_f32_e32 v35, v33, v8
	v_sub_f32_e32 v8, v33, v30
	v_add_f32_e32 v30, v37, v35
	v_sub_f32_e32 v33, v30, v37
	v_sub_f32_e32 v37, v32, v30
	v_sub_f32_e32 v32, v32, v37
	v_sub_f32_e32 v30, v32, v30
	v_sub_f32_e32 v33, v33, v35
	v_add_f32_e32 v28, v28, v30
	v_add_f32_e32 v28, v33, v28
	v_add_f32_e32 v28, v37, v28
	v_mul_f32_e32 v28, v31, v28
	v_add_f32_e32 v8, v8, v28
	v_add_f32_e32 v28, v34, v8
	v_mul_f32_e32 v30, v28, v28
	v_fmamk_f32 v33, v30, 0x3e9b6dac, v21
	v_sub_f32_e32 v31, v28, v34
	v_ldexp_f32 v32, v28, 1
	v_mul_f32_e32 v28, v28, v30
	v_fmaak_f32 v30, v30, v33, 0x3f2aaada
	v_mul_f32_e32 v28, v28, v30
	v_add_f32_e32 v30, v32, v28
	v_sub_f32_e32 v8, v8, v31
	v_sub_f32_e32 v31, v30, v32
	v_ldexp_f32 v8, v8, 1
	v_sub_f32_e32 v28, v28, v31
	v_add_f32_e32 v8, v8, v28
	v_add_f32_e32 v28, v30, v8
	v_sub_f32_e32 v30, v28, v30
	v_add_f32_e32 v31, v36, v28
	v_sub_f32_e32 v8, v8, v30
	v_sub_f32_e32 v30, v31, v36
	v_sub_f32_e32 v32, v31, v30
	v_sub_f32_e32 v28, v28, v30
	v_add_f32_e32 v30, v29, v8
	v_sub_f32_e32 v32, v36, v32
	v_sub_f32_e32 v33, v30, v29
	v_add_f32_e32 v28, v28, v32
	v_sub_f32_e32 v32, v30, v33
	v_sub_f32_e32 v8, v8, v33
	v_sub_f32_e32 v29, v29, v32
	v_add_f32_e32 v28, v30, v28
	v_add_f32_e32 v8, v8, v29
	v_add_f32_e32 v29, v31, v28
	v_sub_f32_e32 v30, v29, v31
	v_sub_f32_e32 v28, v28, v30
	v_add_f32_e32 v8, v8, v28
	v_add_f32_e32 v8, v29, v8
	v_cmp_neq_f32_e64 s[4:5], s21, v25
	s_nop 1
	v_cndmask_b32_e64 v8, v22, v8, s[4:5]
	v_cmp_ngt_f32_e64 s[4:5], -1.0, v25
	s_nop 1
	v_cndmask_b32_e64 v8, v23, v8, s[4:5]
	v_cmp_neq_f32_e64 s[4:5], -1.0, v25
	s_nop 1
	v_cndmask_b32_e64 v8, v24, v8, s[4:5]
	v_cmp_lt_f32_e64 s[4:5], |v25|, s22
	s_nop 1
	v_cndmask_b32_e64 v8, v8, v25, s[4:5]
	v_sub_f32_e32 v2, v2, v8
	v_mul_f32_e32 v2, 0x3fb8aa3b, v2
	global_store_dword v[26:27], v2, off
	global_load_dwordx4 v[26:29], v[42:43], off
	s_nop 0
	global_load_dwordx4 v[30:33], v[42:43], off offset:16
	global_load_dwordx4 v[34:37], v[42:43], off offset:32
	global_load_dwordx4 v[38:41], v[42:43], off offset:48
	v_bitop3_b32 v2, v14, s24, 1 bitop3:0xc8
	v_or_b32_e32 v42, 2, v14
	v_ashrrev_i32_e32 v43, 31, v42
	s_waitcnt vmcnt(3)
; #define GAS __attribute__((address_space(1)))
; __device__ __forceinline__ void phase_inproj() {
;     ...
;           for (int i = 0; i < 4; ++i) {
;             const int row = r0 + fq_ * 4 + i;
;             const GAS f32x4* sp = (const GAS f32x4*)(ssq + (size_t)row * 16);
;             const f32x4 s0 = sp[0], s1 = sp[1], s2 = sp[2], s3 = sp[3];
;             const float t = ((s0.x + s0.y) + (s0.z + s0.w)) + ((s1.x + s1.y) + (s1.z + s1.w)) + ((s2.x + s2.y) + (s2.z + s2.w)) + ((s3.x + s3.y) + (s3.z + s3.w));
;             const float l = c[i] * rsqrtf(t * (1.f / DM) + EPS) + bias;
;             const float ls = fminf(l, 0.f) - log1pf(__expf(-fabsf(l)));
;             logf2[(size_t)((row >> 13) * 8 + fr_) * SEQ + (row & (SEQ - 1))] = ls * LOG2E;
;           }
	v_mov_b32_e32 v44, v27
	v_mov_b32_e32 v45, v28
	v_mov_b32_e32 v27, v29
	s_waitcnt vmcnt(2)
	v_mov_b32_e32 v28, v31
	v_mov_b32_e32 v29, v32
	v_mov_b32_e32 v31, v33
	v_pk_add_f32 v[26:27], v[44:45], v[26:27]
	v_pk_add_f32 v[28:29], v[28:29], v[30:31]
	v_pk_add_f32 v[26:27], v[26:27], v[26:27] op_sel:[0,1] op_sel_hi:[1,0]
	v_pk_add_f32 v[28:29], v[28:29], v[28:29] op_sel:[0,1] op_sel_hi:[1,0]
	s_waitcnt vmcnt(1)
	v_add_f32_e32 v32, v34, v35
	v_add_f32_e32 v34, v36, v37
	s_waitcnt vmcnt(0)
	v_mov_b32_e32 v33, v40
	v_mov_b32_e32 v35, v41
	v_mov_b32_e32 v27, v38
	v_mov_b32_e32 v29, v39
	v_pk_add_f32 v[30:31], v[32:33], v[34:35]
	v_pk_add_f32 v[26:27], v[26:27], v[28:29]
	s_nop 0
	v_pk_add_f32 v[26:27], v[26:27], v[30:31]
	s_nop 0
	v_add_f32_e32 v8, v26, v27
	v_fmamk_f32 v8, v8, 0x3a800000, v20
	v_mul_f32_e32 v25, 0x4b800000, v8
	v_cmp_gt_f32_e64 s[4:5], s3, v8
	v_lshlrev_b64 v[26:27], 6, v[42:43]
	v_lshl_add_u64 v[42:43], s[8:9], 0, v[26:27]
	v_cndmask_b32_e64 v8, v8, v25, s[4:5]
	v_rsq_f32_e32 v8, v8
	s_nop 0
	v_mul_f32_e32 v25, 0x45800000, v8
	v_cndmask_b32_e64 v8, v8, v25, s[4:5]
	v_fma_f32 v25, v3, v8, v15
	v_mul_f32_e64 v3, |v25|, s18
	v_exp_f32_e32 v28, v3
	v_lshlrev_b32_e32 v8, 2, v2
	v_lshl_add_u64 v[2:3], v[16:17], 0, v[8:9]
	v_min_f32_e32 v8, 0, v25
	v_add_f32_e32 v25, 1.0, v28
	v_add_f32_e32 v29, -1.0, v25
	v_frexp_mant_f32_e32 v30, v25
	v_cvt_f64_f32_e32 v[26:27], v25
	v_sub_f32_e32 v31, v29, v25
	v_frexp_exp_i32_f64_e32 v26, v[26:27]
	v_cmp_gt_f32_e64 s[4:5], s19, v30
	v_sub_f32_e32 v29, v28, v29
	v_add_f32_e32 v27, 1.0, v31
	v_subbrev_co_u32_e64 v26, s[4:5], 0, v26, s[4:5]
	v_add_f32_e32 v27, v29, v27
	v_sub_u32_e32 v29, 0, v26
	v_cvt_f32_i32_e32 v26, v26
	v_ldexp_f32 v25, v25, v29
	v_ldexp_f32 v27, v27, v29
	v_add_f32_e32 v29, -1.0, v25
	v_add_f32_e32 v30, 1.0, v25
	v_add_f32_e32 v31, 1.0, v29
	v_add_f32_e32 v32, -1.0, v30
	v_sub_f32_e32 v31, v25, v31
	v_sub_f32_e32 v25, v25, v32
	v_mul_f32_e32 v32, 0x3f317218, v26
	v_add_f32_e32 v31, v27, v31
	v_add_f32_e32 v25, v27, v25
	v_fma_f32 v27, v26, s20, -v32
	v_add_f32_e32 v33, v29, v31
	v_add_f32_e32 v34, v30, v25
	v_fmac_f32_e32 v27, 0xb102e308, v26
	v_sub_f32_e32 v26, v33, v29
	v_sub_f32_e32 v29, v34, v30
	v_rcp_f32_e32 v30, v34
	v_add_f32_e32 v35, v32, v27
	v_sub_f32_e32 v25, v25, v29
	v_sub_f32_e32 v29, v35, v32
	v_sub_f32_e32 v27, v27, v29
	v_mul_f32_e32 v29, v33, v30
	v_sub_f32_e32 v26, v31, v26
	v_mul_f32_e32 v31, v34, v29
	v_fma_f32 v32, v29, v34, -v31
	v_fmac_f32_e32 v32, v29, v25
	v_add_f32_e32 v36, v31, v32
	v_sub_f32_e32 v37, v33, v36
	v_sub_f32_e32 v31, v36, v31
	v_sub_f32_e32 v33, v33, v37
	v_sub_f32_e32 v31, v31, v32
	v_sub_f32_e32 v32, v33, v36
	v_add_f32_e32 v26, v26, v32
	v_add_f32_e32 v26, v31, v26
	v_add_f32_e32 v31, v37, v26
	v_mul_f32_e32 v32, v30, v31
	v_sub_f32_e32 v33, v37, v31
	v_mul_f32_e32 v36, v34, v32
	v_add_f32_e32 v26, v26, v33
	v_add_f32_e32 v33, v29, v32
	v_fma_f32 v34, v32, v34, -v36
	v_sub_f32_e32 v29, v33, v29
	v_fmac_f32_e32 v34, v32, v25
	v_sub_f32_e32 v25, v32, v29
	v_add_f32_e32 v29, v36, v34
	v_sub_f32_e32 v32, v29, v36
	v_sub_f32_e32 v36, v31, v29
	v_sub_f32_e32 v31, v31, v36
	v_sub_f32_e32 v29, v31, v29
	v_sub_f32_e32 v32, v32, v34
	v_add_f32_e32 v26, v26, v29
	v_add_f32_e32 v26, v32, v26
	v_add_f32_e32 v26, v36, v26
	v_mul_f32_e32 v26, v30, v26
	v_add_f32_e32 v25, v25, v26
	v_add_f32_e32 v26, v33, v25
	v_mul_f32_e32 v29, v26, v26
	v_fmamk_f32 v32, v29, 0x3e9b6dac, v21
	v_sub_f32_e32 v30, v26, v33
	v_ldexp_f32 v31, v26, 1
	v_mul_f32_e32 v26, v26, v29
	v_fmaak_f32 v29, v29, v32, 0x3f2aaada
	v_mul_f32_e32 v26, v26, v29
	v_add_f32_e32 v29, v31, v26
	v_sub_f32_e32 v25, v25, v30
	v_sub_f32_e32 v30, v29, v31
	v_ldexp_f32 v25, v25, 1
	v_sub_f32_e32 v26, v26, v30
	v_add_f32_e32 v25, v25, v26
	v_add_f32_e32 v26, v29, v25
	v_sub_f32_e32 v29, v26, v29
	v_add_f32_e32 v30, v35, v26
	v_sub_f32_e32 v25, v25, v29
	v_sub_f32_e32 v29, v30, v35
	v_sub_f32_e32 v31, v30, v29
	v_sub_f32_e32 v26, v26, v29
	v_add_f32_e32 v29, v27, v25
	v_sub_f32_e32 v31, v35, v31
	v_sub_f32_e32 v32, v29, v27
	v_add_f32_e32 v26, v26, v31
	v_sub_f32_e32 v31, v29, v32
	v_sub_f32_e32 v25, v25, v32
	v_sub_f32_e32 v27, v27, v31
	v_add_f32_e32 v26, v29, v26
	v_add_f32_e32 v25, v25, v27
	v_add_f32_e32 v27, v30, v26
	v_sub_f32_e32 v29, v27, v30
	v_sub_f32_e32 v26, v26, v29
	v_add_f32_e32 v25, v25, v26
	v_add_f32_e32 v25, v27, v25
	v_cmp_neq_f32_e64 s[4:5], s21, v28
	s_nop 1
	v_cndmask_b32_e64 v25, v22, v25, s[4:5]
	v_cmp_ngt_f32_e64 s[4:5], -1.0, v28
	s_nop 1
	v_cndmask_b32_e64 v25, v23, v25, s[4:5]
	v_cmp_neq_f32_e64 s[4:5], -1.0, v28
	s_nop 1
	v_cndmask_b32_e64 v25, v24, v25, s[4:5]
	v_cmp_lt_f32_e64 s[4:5], |v28|, s22
	s_nop 1
	v_cndmask_b32_e64 v25, v25, v28, s[4:5]
	v_sub_f32_e32 v8, v8, v25
	v_mul_f32_e32 v8, 0x3fb8aa3b, v8
	global_store_dword v[2:3], v8, off
	global_load_dwordx4 v[26:29], v[42:43], off
	global_load_dwordx4 v[30:33], v[42:43], off offset:16
	global_load_dwordx4 v[34:37], v[42:43], off offset:32
	global_load_dwordx4 v[38:41], v[42:43], off offset:48
	v_bitop3_b32 v8, v14, s25, 2 bitop3:0xc8
	v_lshlrev_b32_e32 v8, 2, v8
	v_or_b32_e32 v2, 3, v14
	s_waitcnt vmcnt(3)
	v_mov_b32_e32 v42, v27
	v_mov_b32_e32 v43, v28
	v_mov_b32_e32 v27, v29
	s_waitcnt vmcnt(2)
	v_mov_b32_e32 v28, v31
	v_mov_b32_e32 v29, v32
	v_mov_b32_e32 v31, v33
	v_pk_add_f32 v[26:27], v[42:43], v[26:27]
	v_pk_add_f32 v[28:29], v[28:29], v[30:31]
	v_pk_add_f32 v[26:27], v[26:27], v[26:27] op_sel:[0,1] op_sel_hi:[1,0]
	v_pk_add_f32 v[28:29], v[28:29], v[28:29] op_sel:[0,1] op_sel_hi:[1,0]
	s_waitcnt vmcnt(1)
	v_add_f32_e32 v32, v34, v35
	v_add_f32_e32 v34, v36, v37
	s_waitcnt vmcnt(0)
; #define GAS __attribute__((address_space(1)))
; __device__ __forceinline__ void phase_inproj() {
;     ...
;           for (int i = 0; i < 4; ++i) {
;             const int row = r0 + fq_ * 4 + i;
;             const GAS f32x4* sp = (const GAS f32x4*)(ssq + (size_t)row * 16);
;             const f32x4 s0 = sp[0], s1 = sp[1], s2 = sp[2], s3 = sp[3];
;             const float t = ((s0.x + s0.y) + (s0.z + s0.w)) + ((s1.x + s1.y) + (s1.z + s1.w)) + ((s2.x + s2.y) + (s2.z + s2.w)) + ((s3.x + s3.y) + (s3.z + s3.w));
;             const float l = c[i] * rsqrtf(t * (1.f / DM) + EPS) + bias;
;             const float ls = fminf(l, 0.f) - log1pf(__expf(-fabsf(l)));
;             logf2[(size_t)((row >> 13) * 8 + fr_) * SEQ + (row & (SEQ - 1))] = ls * LOG2E;
;           }
	v_mov_b32_e32 v33, v40
	v_mov_b32_e32 v35, v41
	v_mov_b32_e32 v27, v38
	v_mov_b32_e32 v29, v39
	v_pk_add_f32 v[30:31], v[32:33], v[34:35]
	v_pk_add_f32 v[26:27], v[26:27], v[28:29]
	s_nop 0
	v_pk_add_f32 v[26:27], v[26:27], v[30:31]
	s_nop 0
	v_add_f32_e32 v3, v26, v27
	v_fmamk_f32 v3, v3, 0x3a800000, v20
	v_mul_f32_e32 v25, 0x4b800000, v3
	v_cmp_gt_f32_e64 s[4:5], s3, v3
	s_nop 1
	v_cndmask_b32_e64 v3, v3, v25, s[4:5]
	v_rsq_f32_e32 v25, v3
	v_ashrrev_i32_e32 v3, 31, v2
	v_lshlrev_b64 v[2:3], 6, v[2:3]
	v_lshl_add_u64 v[2:3], s[8:9], 0, v[2:3]
	v_mul_f32_e32 v26, 0x45800000, v25
	v_cndmask_b32_e64 v25, v25, v26, s[4:5]
	v_fma_f32 v4, v4, v25, v15
	v_mul_f32_e64 v25, |v4|, s18
	v_exp_f32_e32 v25, v25
	v_lshl_add_u64 v[26:27], v[16:17], 0, v[8:9]
	v_min_f32_e32 v4, 0, v4
	v_add_f32_e32 v8, 1.0, v25
	v_add_f32_e32 v30, -1.0, v8
	v_frexp_mant_f32_e32 v31, v8
	v_cvt_f64_f32_e32 v[28:29], v8
	v_sub_f32_e32 v32, v30, v8
	v_frexp_exp_i32_f64_e32 v28, v[28:29]
	v_cmp_gt_f32_e64 s[4:5], s19, v31
	v_sub_f32_e32 v30, v25, v30
	v_add_f32_e32 v29, 1.0, v32
	v_subbrev_co_u32_e64 v28, s[4:5], 0, v28, s[4:5]
	v_add_f32_e32 v29, v30, v29
	v_sub_u32_e32 v30, 0, v28
	v_cvt_f32_i32_e32 v28, v28
	v_ldexp_f32 v8, v8, v30
	v_ldexp_f32 v29, v29, v30
	v_add_f32_e32 v30, -1.0, v8
	v_add_f32_e32 v31, 1.0, v8
	v_add_f32_e32 v32, 1.0, v30
	v_add_f32_e32 v33, -1.0, v31
	v_sub_f32_e32 v32, v8, v32
	v_sub_f32_e32 v8, v8, v33
	v_mul_f32_e32 v33, 0x3f317218, v28
	v_add_f32_e32 v32, v29, v32
	v_add_f32_e32 v8, v29, v8
	v_fma_f32 v29, v28, s20, -v33
	v_add_f32_e32 v34, v30, v32
	v_add_f32_e32 v35, v31, v8
	v_fmac_f32_e32 v29, 0xb102e308, v28
	v_sub_f32_e32 v28, v34, v30
	v_sub_f32_e32 v30, v35, v31
	v_rcp_f32_e32 v31, v35
	v_add_f32_e32 v36, v33, v29
	v_sub_f32_e32 v8, v8, v30
	v_sub_f32_e32 v30, v36, v33
	v_sub_f32_e32 v29, v29, v30
	v_mul_f32_e32 v30, v34, v31
	v_sub_f32_e32 v28, v32, v28
	v_mul_f32_e32 v32, v35, v30
	v_fma_f32 v33, v30, v35, -v32
	v_fmac_f32_e32 v33, v30, v8
	v_add_f32_e32 v37, v32, v33
	v_sub_f32_e32 v38, v34, v37
	v_sub_f32_e32 v32, v37, v32
	v_sub_f32_e32 v34, v34, v38
	v_sub_f32_e32 v32, v32, v33
	v_sub_f32_e32 v33, v34, v37
	v_add_f32_e32 v28, v28, v33
	v_add_f32_e32 v28, v32, v28
	v_add_f32_e32 v32, v38, v28
	v_mul_f32_e32 v33, v31, v32
	v_sub_f32_e32 v34, v38, v32
	v_mul_f32_e32 v37, v35, v33
	v_add_f32_e32 v28, v28, v34
	v_add_f32_e32 v34, v30, v33
	v_fma_f32 v35, v33, v35, -v37
	v_sub_f32_e32 v30, v34, v30
	v_fmac_f32_e32 v35, v33, v8
	v_sub_f32_e32 v8, v33, v30
	v_add_f32_e32 v30, v37, v35
	v_sub_f32_e32 v33, v30, v37
	v_sub_f32_e32 v37, v32, v30
	v_sub_f32_e32 v32, v32, v37
	v_sub_f32_e32 v30, v32, v30
	v_sub_f32_e32 v33, v33, v35
	v_add_f32_e32 v28, v28, v30
	v_add_f32_e32 v28, v33, v28
	v_add_f32_e32 v28, v37, v28
	v_mul_f32_e32 v28, v31, v28
	v_add_f32_e32 v8, v8, v28
	v_add_f32_e32 v28, v34, v8
	v_mul_f32_e32 v30, v28, v28
	v_fmamk_f32 v33, v30, 0x3e9b6dac, v21
	v_sub_f32_e32 v31, v28, v34
	v_ldexp_f32 v32, v28, 1
	v_mul_f32_e32 v28, v28, v30
	v_fmaak_f32 v30, v30, v33, 0x3f2aaada
	v_mul_f32_e32 v28, v28, v30
	v_add_f32_e32 v30, v32, v28
	v_sub_f32_e32 v8, v8, v31
	v_sub_f32_e32 v31, v30, v32
	v_ldexp_f32 v8, v8, 1
	v_sub_f32_e32 v28, v28, v31
	v_add_f32_e32 v8, v8, v28
	v_add_f32_e32 v28, v30, v8
	v_sub_f32_e32 v30, v28, v30
	v_add_f32_e32 v31, v36, v28
	v_sub_f32_e32 v8, v8, v30
	v_sub_f32_e32 v30, v31, v36
	v_sub_f32_e32 v32, v31, v30
	v_sub_f32_e32 v28, v28, v30
	v_add_f32_e32 v30, v29, v8
	v_sub_f32_e32 v32, v36, v32
	v_sub_f32_e32 v33, v30, v29
	v_add_f32_e32 v28, v28, v32
	v_sub_f32_e32 v32, v30, v33
	v_sub_f32_e32 v8, v8, v33
	v_sub_f32_e32 v29, v29, v32
	v_add_f32_e32 v28, v30, v28
	v_add_f32_e32 v8, v8, v29
	v_add_f32_e32 v29, v31, v28
	v_sub_f32_e32 v30, v29, v31
	v_sub_f32_e32 v28, v28, v30
	v_add_f32_e32 v8, v8, v28
	v_add_f32_e32 v8, v29, v8
	v_cmp_neq_f32_e64 s[4:5], s21, v25
	s_nop 1
	v_cndmask_b32_e64 v8, v22, v8, s[4:5]
	v_cmp_ngt_f32_e64 s[4:5], -1.0, v25
	s_nop 1
	v_cndmask_b32_e64 v8, v23, v8, s[4:5]
	v_cmp_neq_f32_e64 s[4:5], -1.0, v25
	s_nop 1
	v_cndmask_b32_e64 v8, v24, v8, s[4:5]
	v_cmp_lt_f32_e64 s[4:5], |v25|, s22
	s_nop 1
	v_cndmask_b32_e64 v8, v8, v25, s[4:5]
	v_sub_f32_e32 v4, v4, v8
	v_mul_f32_e32 v4, 0x3fb8aa3b, v4
	global_store_dword v[26:27], v4, off
	global_load_dwordx4 v[26:29], v[2:3], off
	s_nop 0
	global_load_dwordx4 v[30:33], v[2:3], off offset:16
	global_load_dwordx4 v[34:37], v[2:3], off offset:32
	global_load_dwordx4 v[38:41], v[2:3], off offset:48
	s_waitcnt vmcnt(3)
	v_mov_b32_e32 v2, v27
	v_mov_b32_e32 v3, v28
	v_mov_b32_e32 v27, v29
	s_waitcnt vmcnt(2)
; #define GAS __attribute__((address_space(1)))
; __device__ __forceinline__ void phase_inproj() {
;     ...
;           for (int i = 0; i < 4; ++i) {
;             const int row = r0 + fq_ * 4 + i;
;             const GAS f32x4* sp = (const GAS f32x4*)(ssq + (size_t)row * 16);
;             const f32x4 s0 = sp[0], s1 = sp[1], s2 = sp[2], s3 = sp[3];
;             const float t = ((s0.x + s0.y) + (s0.z + s0.w)) + ((s1.x + s1.y) + (s1.z + s1.w)) + ((s2.x + s2.y) + (s2.z + s2.w)) + ((s3.x + s3.y) + (s3.z + s3.w));
;             const float l = c[i] * rsqrtf(t * (1.f / DM) + EPS) + bias;
;             const float ls = fminf(l, 0.f) - log1pf(__expf(-fabsf(l)));
;             logf2[(size_t)((row >> 13) * 8 + fr_) * SEQ + (row & (SEQ - 1))] = ls * LOG2E;
;           }
	v_mov_b32_e32 v28, v31
	v_mov_b32_e32 v29, v32
	v_mov_b32_e32 v31, v33
	v_pk_add_f32 v[2:3], v[2:3], v[26:27]
	v_pk_add_f32 v[26:27], v[28:29], v[30:31]
	v_pk_add_f32 v[2:3], v[2:3], v[2:3] op_sel:[0,1] op_sel_hi:[1,0]
	v_pk_add_f32 v[26:27], v[26:27], v[26:27] op_sel:[0,1] op_sel_hi:[1,0]
	s_waitcnt vmcnt(1)
	v_add_f32_e32 v32, v34, v35
	v_add_f32_e32 v34, v36, v37
	s_waitcnt vmcnt(0)
	v_mov_b32_e32 v33, v40
	v_mov_b32_e32 v35, v41
	v_mov_b32_e32 v3, v38
	v_mov_b32_e32 v27, v39
	v_pk_add_f32 v[28:29], v[32:33], v[34:35]
	v_pk_add_f32 v[2:3], v[2:3], v[26:27]
	s_nop 0
	v_pk_add_f32 v[2:3], v[2:3], v[28:29]
	s_nop 0
	v_add_f32_e32 v2, v2, v3
	v_fmamk_f32 v2, v2, 0x3a800000, v20
	v_mul_f32_e32 v3, 0x4b800000, v2
	v_cmp_gt_f32_e64 s[4:5], s3, v2
	s_nop 1
	v_cndmask_b32_e64 v2, v2, v3, s[4:5]
	v_rsq_f32_e32 v2, v2
	s_nop 0
	v_mul_f32_e32 v3, 0x45800000, v2
	v_cndmask_b32_e64 v2, v2, v3, s[4:5]
	v_fmac_f32_e32 v15, v5, v2
	v_mul_f32_e64 v2, |v15|, s18
	v_exp_f32_e32 v4, v2
	v_bitop3_b32 v2, v14, s26, 3 bitop3:0xc8
	v_lshlrev_b32_e32 v8, 2, v2
	v_min_f32_e32 v5, 0, v15
	v_add_f32_e32 v14, 1.0, v4
	v_add_f32_e32 v15, -1.0, v14
	v_frexp_mant_f32_e32 v25, v14
	v_cvt_f64_f32_e32 v[2:3], v14
	v_sub_f32_e32 v26, v15, v14
	v_frexp_exp_i32_f64_e32 v2, v[2:3]
	v_cmp_gt_f32_e64 s[4:5], s19, v25
	v_sub_f32_e32 v15, v4, v15
	v_add_f32_e32 v3, 1.0, v26
	v_subbrev_co_u32_e64 v2, s[4:5], 0, v2, s[4:5]
	v_add_f32_e32 v3, v15, v3
	v_sub_u32_e32 v15, 0, v2
	v_cvt_f32_i32_e32 v2, v2
	v_ldexp_f32 v14, v14, v15
	v_ldexp_f32 v3, v3, v15
	v_add_f32_e32 v15, -1.0, v14
	v_add_f32_e32 v25, 1.0, v14
	v_add_f32_e32 v26, 1.0, v15
	v_add_f32_e32 v27, -1.0, v25
	v_sub_f32_e32 v26, v14, v26
	v_sub_f32_e32 v14, v14, v27
	v_mul_f32_e32 v27, 0x3f317218, v2
	v_add_f32_e32 v26, v3, v26
	v_add_f32_e32 v3, v3, v14
	v_fma_f32 v14, v2, s20, -v27
	v_add_f32_e32 v28, v15, v26
	v_add_f32_e32 v29, v25, v3
	v_fmac_f32_e32 v14, 0xb102e308, v2
	v_sub_f32_e32 v2, v28, v15
	v_sub_f32_e32 v15, v29, v25
	v_rcp_f32_e32 v25, v29
	v_add_f32_e32 v30, v27, v14
	v_sub_f32_e32 v3, v3, v15
	v_sub_f32_e32 v15, v30, v27
	v_sub_f32_e32 v14, v14, v15
	v_mul_f32_e32 v15, v28, v25
	v_sub_f32_e32 v2, v26, v2
	v_mul_f32_e32 v26, v29, v15
	v_fma_f32 v27, v15, v29, -v26
	v_fmac_f32_e32 v27, v15, v3
	v_add_f32_e32 v31, v26, v27
	v_sub_f32_e32 v32, v28, v31
	v_sub_f32_e32 v26, v31, v26
	v_sub_f32_e32 v28, v28, v32
	v_sub_f32_e32 v26, v26, v27
	v_sub_f32_e32 v27, v28, v31
	v_add_f32_e32 v2, v2, v27
	v_add_f32_e32 v2, v26, v2
	v_add_f32_e32 v26, v32, v2
	v_mul_f32_e32 v27, v25, v26
	v_sub_f32_e32 v28, v32, v26
	v_mul_f32_e32 v31, v29, v27
	v_add_f32_e32 v2, v2, v28
	v_add_f32_e32 v28, v15, v27
	v_fma_f32 v29, v27, v29, -v31
	v_sub_f32_e32 v15, v28, v15
	v_fmac_f32_e32 v29, v27, v3
	v_sub_f32_e32 v3, v27, v15
	v_add_f32_e32 v15, v31, v29
	v_sub_f32_e32 v27, v15, v31
	v_sub_f32_e32 v31, v26, v15
	v_sub_f32_e32 v26, v26, v31
	v_sub_f32_e32 v15, v26, v15
	v_sub_f32_e32 v27, v27, v29
	v_add_f32_e32 v2, v2, v15
	v_add_f32_e32 v2, v27, v2
	v_add_f32_e32 v2, v31, v2
	v_mul_f32_e32 v2, v25, v2
	v_add_f32_e32 v2, v3, v2
	v_add_f32_e32 v3, v28, v2
	v_mul_f32_e32 v15, v3, v3
	v_fmamk_f32 v27, v15, 0x3e9b6dac, v21
	v_sub_f32_e32 v25, v3, v28
	v_ldexp_f32 v26, v3, 1
	v_mul_f32_e32 v3, v3, v15
	v_fmaak_f32 v15, v15, v27, 0x3f2aaada
	v_mul_f32_e32 v3, v3, v15
	v_add_f32_e32 v15, v26, v3
	v_sub_f32_e32 v2, v2, v25
	v_sub_f32_e32 v25, v15, v26
	v_ldexp_f32 v2, v2, 1
	v_sub_f32_e32 v3, v3, v25
	v_add_f32_e32 v2, v2, v3
	v_add_f32_e32 v3, v15, v2
	v_sub_f32_e32 v15, v3, v15
	v_add_f32_e32 v25, v30, v3
	v_sub_f32_e32 v2, v2, v15
	v_sub_f32_e32 v15, v25, v30
	v_sub_f32_e32 v26, v25, v15
	v_sub_f32_e32 v3, v3, v15
	v_add_f32_e32 v15, v14, v2
	v_sub_f32_e32 v26, v30, v26
	v_sub_f32_e32 v27, v15, v14
	v_add_f32_e32 v3, v3, v26
	v_sub_f32_e32 v26, v15, v27
	v_sub_f32_e32 v2, v2, v27
	v_sub_f32_e32 v14, v14, v26
	v_add_f32_e32 v3, v15, v3
	v_add_f32_e32 v2, v2, v14
	v_add_f32_e32 v14, v25, v3
	v_sub_f32_e32 v15, v14, v25
	v_sub_f32_e32 v3, v3, v15
	v_add_f32_e32 v2, v2, v3
	v_add_f32_e32 v2, v14, v2
	v_cmp_neq_f32_e64 s[4:5], s21, v4
	s_nop 1
	v_cndmask_b32_e64 v2, v22, v2, s[4:5]
	v_cmp_ngt_f32_e64 s[4:5], -1.0, v4
	s_nop 1
	v_cndmask_b32_e64 v2, v23, v2, s[4:5]
	v_cmp_neq_f32_e64 s[4:5], -1.0, v4
	s_nop 1
	v_cndmask_b32_e64 v2, v24, v2, s[4:5]
	v_cmp_lt_f32_e64 s[4:5], |v4|, s22
	s_nop 1
	v_cndmask_b32_e64 v2, v2, v4, s[4:5]
	v_sub_f32_e32 v2, v5, v2
	v_mul_f32_e32 v4, 0x3fb8aa3b, v2
	v_lshl_add_u64 v[2:3], v[16:17], 0, v[8:9]
	global_store_dword v[2:3], v4, off
	s_branch .LBB0_377
